# phase 0 copy of the cache conversion: 32 serialized load-wait-store round trips batched into two groups of 16 loads
# speedup vs baseline: 1.0077x; 1.0011x over previous
.LBB0_56:
	s_or_b64 exec, exec, s[2:3]
	s_load_dwordx8 s[36:43], s[20:21], 0x10
	s_waitcnt lgkmcnt(0)
	v_lshl_add_u64 v[20:21], s[24:25], 0, v[10:11]
	s_mov_b64 s[2:3], 0x14100000
	v_lshl_add_u64 v[6:7], v[20:21], 0, s[2:3]
	s_mov_b64 s[2:3], 0x14380000
	v_lshl_add_u64 v[12:13], v[20:21], 0, s[2:3]
	s_mov_b64 s[2:3], 0x15600000
	v_lshl_add_u64 v[16:17], v[20:21], 0, s[2:3]
	s_mov_b64 s[2:3], 0x15d00000
	v_lshl_add_u64 v[10:11], s[36:37], 0, v[22:23]
	v_lshl_add_u64 v[14:15], s[38:39], 0, v[22:23]
	v_lshl_add_u64 v[18:19], s[40:41], 0, v[22:23]
	v_lshl_add_u64 v[20:21], v[20:21], 0, s[2:3]
	v_lshl_add_u64 v[22:23], s[42:43], 0, v[22:23]
	s_mov_b32 s18, 0
	s_mov_b64 s[10:11], 0x3fff
	s_mov_b64 s[20:21], 0xfff
	s_mov_b64 s[22:23], 0x20000
	s_mov_b64 s[24:25], 0x100000
	s_mov_b64 s[26:27], 0x8000
	s_mov_b64 s[28:29], 0x40000
	s_cmp_lt_u32 s8, 0x4000
	s_cbranch_scc1 .LBB0_58
	s_and_saveexec_b64 s[2:3], s[4:5]
	global_load_dwordx4 v[132:135], v[10:11], off
	global_load_dwordx4 v[140:143], v[18:19], off
	global_load_dwordx4 v[144:147], v[22:23], off
	v_lshl_add_u64 v[10:11], v[10:11], 0, s[24:25]
	v_lshl_add_u64 v[18:19], v[18:19], 0, s[24:25]
	v_lshl_add_u64 v[22:23], v[22:23], 0, s[24:25]
	global_load_dwordx4 v[148:151], v[10:11], off
	global_load_dwordx4 v[156:159], v[18:19], off
	global_load_dwordx4 v[160:163], v[22:23], off
	v_lshl_add_u64 v[10:11], v[10:11], 0, s[24:25]
	v_lshl_add_u64 v[18:19], v[18:19], 0, s[24:25]
	v_lshl_add_u64 v[22:23], v[22:23], 0, s[24:25]
	global_load_dwordx4 v[164:167], v[10:11], off
	global_load_dwordx4 v[172:175], v[18:19], off
	global_load_dwordx4 v[176:179], v[22:23], off
	v_lshl_add_u64 v[10:11], v[10:11], 0, s[24:25]
	v_lshl_add_u64 v[18:19], v[18:19], 0, s[24:25]
	v_lshl_add_u64 v[22:23], v[22:23], 0, s[24:25]
	global_load_dwordx4 v[180:183], v[10:11], off
	global_load_dwordx4 v[188:191], v[18:19], off
	global_load_dwordx4 v[192:195], v[22:23], off
	v_lshl_add_u64 v[10:11], v[10:11], 0, s[24:25]
	v_lshl_add_u64 v[18:19], v[18:19], 0, s[24:25]
	v_lshl_add_u64 v[22:23], v[22:23], 0, s[24:25]
	s_or_b64 exec, exec, s[2:3]
	s_and_saveexec_b64 s[2:3], vcc
	global_load_dwordx4 v[136:139], v[14:15], off
	v_lshl_add_u64 v[14:15], v[14:15], 0, s[28:29]
	global_load_dwordx4 v[152:155], v[14:15], off
	v_lshl_add_u64 v[14:15], v[14:15], 0, s[28:29]
	global_load_dwordx4 v[168:171], v[14:15], off
	v_lshl_add_u64 v[14:15], v[14:15], 0, s[28:29]
	global_load_dwordx4 v[184:187], v[14:15], off
	v_lshl_add_u64 v[14:15], v[14:15], 0, s[28:29]
	s_or_b64 exec, exec, s[2:3]
	s_waitcnt vmcnt(0)
	s_and_saveexec_b64 s[2:3], s[4:5]
	v_cvt_pk_bf16_f32 v132, v132, v133
	v_cvt_pk_bf16_f32 v133, v134, v135
	global_store_dwordx2 v[6:7], v[132:133], off
	v_lshl_add_u64 v[6:7], v[6:7], 0, s[22:23]
	v_cvt_pk_bf16_f32 v140, v140, v141
	v_cvt_pk_bf16_f32 v141, v142, v143
	global_store_dwordx2 v[16:17], v[140:141], off
	v_lshl_add_u64 v[16:17], v[16:17], 0, s[22:23]
	v_cvt_pk_bf16_f32 v144, v144, v145
	v_cvt_pk_bf16_f32 v145, v146, v147
	global_store_dwordx2 v[20:21], v[144:145], off
	v_lshl_add_u64 v[20:21], v[20:21], 0, s[22:23]
	v_cvt_pk_bf16_f32 v148, v148, v149
	v_cvt_pk_bf16_f32 v149, v150, v151
	global_store_dwordx2 v[6:7], v[148:149], off
	v_lshl_add_u64 v[6:7], v[6:7], 0, s[22:23]
	v_cvt_pk_bf16_f32 v156, v156, v157
	v_cvt_pk_bf16_f32 v157, v158, v159
	global_store_dwordx2 v[16:17], v[156:157], off
	v_lshl_add_u64 v[16:17], v[16:17], 0, s[22:23]
	v_cvt_pk_bf16_f32 v160, v160, v161
	v_cvt_pk_bf16_f32 v161, v162, v163
	global_store_dwordx2 v[20:21], v[160:161], off
	v_lshl_add_u64 v[20:21], v[20:21], 0, s[22:23]
	v_cvt_pk_bf16_f32 v164, v164, v165
	v_cvt_pk_bf16_f32 v165, v166, v167
	global_store_dwordx2 v[6:7], v[164:165], off
	v_lshl_add_u64 v[6:7], v[6:7], 0, s[22:23]
	v_cvt_pk_bf16_f32 v172, v172, v173
	v_cvt_pk_bf16_f32 v173, v174, v175
	global_store_dwordx2 v[16:17], v[172:173], off
	v_lshl_add_u64 v[16:17], v[16:17], 0, s[22:23]
	v_cvt_pk_bf16_f32 v176, v176, v177
	v_cvt_pk_bf16_f32 v177, v178, v179
	global_store_dwordx2 v[20:21], v[176:177], off
	v_lshl_add_u64 v[20:21], v[20:21], 0, s[22:23]
	v_cvt_pk_bf16_f32 v180, v180, v181
	v_cvt_pk_bf16_f32 v181, v182, v183
	global_store_dwordx2 v[6:7], v[180:181], off
	v_lshl_add_u64 v[6:7], v[6:7], 0, s[22:23]
	v_cvt_pk_bf16_f32 v188, v188, v189
	v_cvt_pk_bf16_f32 v189, v190, v191
	global_store_dwordx2 v[16:17], v[188:189], off
	v_lshl_add_u64 v[16:17], v[16:17], 0, s[22:23]
	v_cvt_pk_bf16_f32 v192, v192, v193
	v_cvt_pk_bf16_f32 v193, v194, v195
	global_store_dwordx2 v[20:21], v[192:193], off
	v_lshl_add_u64 v[20:21], v[20:21], 0, s[22:23]
	s_or_b64 exec, exec, s[2:3]
	s_and_saveexec_b64 s[2:3], vcc
	v_cvt_pk_bf16_f32 v136, v136, v137
	v_cvt_pk_bf16_f32 v137, v138, v139
	global_store_dwordx2 v[12:13], v[136:137], off
	v_lshl_add_u64 v[12:13], v[12:13], 0, s[26:27]
	v_cvt_pk_bf16_f32 v152, v152, v153
	v_cvt_pk_bf16_f32 v153, v154, v155
	global_store_dwordx2 v[12:13], v[152:153], off
	v_lshl_add_u64 v[12:13], v[12:13], 0, s[26:27]
	v_cvt_pk_bf16_f32 v168, v168, v169
	v_cvt_pk_bf16_f32 v169, v170, v171
	global_store_dwordx2 v[12:13], v[168:169], off
	v_lshl_add_u64 v[12:13], v[12:13], 0, s[26:27]
	v_cvt_pk_bf16_f32 v184, v184, v185
	v_cvt_pk_bf16_f32 v185, v186, v187
	global_store_dwordx2 v[12:13], v[184:185], off
	v_lshl_add_u64 v[12:13], v[12:13], 0, s[26:27]
	s_or_b64 exec, exec, s[2:3]
	s_nop 1
	s_and_saveexec_b64 s[2:3], s[4:5]
	global_load_dwordx4 v[132:135], v[10:11], off
	global_load_dwordx4 v[140:143], v[18:19], off
	global_load_dwordx4 v[144:147], v[22:23], off
	v_lshl_add_u64 v[10:11], v[10:11], 0, s[24:25]
	v_lshl_add_u64 v[18:19], v[18:19], 0, s[24:25]
	v_lshl_add_u64 v[22:23], v[22:23], 0, s[24:25]
	global_load_dwordx4 v[148:151], v[10:11], off
	global_load_dwordx4 v[156:159], v[18:19], off
	global_load_dwordx4 v[160:163], v[22:23], off
	v_lshl_add_u64 v[10:11], v[10:11], 0, s[24:25]
	v_lshl_add_u64 v[18:19], v[18:19], 0, s[24:25]
	v_lshl_add_u64 v[22:23], v[22:23], 0, s[24:25]
	global_load_dwordx4 v[164:167], v[10:11], off
	global_load_dwordx4 v[172:175], v[18:19], off
	global_load_dwordx4 v[176:179], v[22:23], off
	v_lshl_add_u64 v[10:11], v[10:11], 0, s[24:25]
	v_lshl_add_u64 v[18:19], v[18:19], 0, s[24:25]
	v_lshl_add_u64 v[22:23], v[22:23], 0, s[24:25]
	global_load_dwordx4 v[180:183], v[10:11], off
	global_load_dwordx4 v[188:191], v[18:19], off
	global_load_dwordx4 v[192:195], v[22:23], off
	v_lshl_add_u64 v[10:11], v[10:11], 0, s[24:25]
	v_lshl_add_u64 v[18:19], v[18:19], 0, s[24:25]
	v_lshl_add_u64 v[22:23], v[22:23], 0, s[24:25]
	s_or_b64 exec, exec, s[2:3]
	s_and_saveexec_b64 s[2:3], vcc
	global_load_dwordx4 v[136:139], v[14:15], off
	v_lshl_add_u64 v[14:15], v[14:15], 0, s[28:29]
	global_load_dwordx4 v[152:155], v[14:15], off
	v_lshl_add_u64 v[14:15], v[14:15], 0, s[28:29]
	global_load_dwordx4 v[168:171], v[14:15], off
	v_lshl_add_u64 v[14:15], v[14:15], 0, s[28:29]
	global_load_dwordx4 v[184:187], v[14:15], off
	v_lshl_add_u64 v[14:15], v[14:15], 0, s[28:29]
	s_or_b64 exec, exec, s[2:3]
	s_waitcnt vmcnt(0)
	s_and_saveexec_b64 s[2:3], s[4:5]
	v_cvt_pk_bf16_f32 v132, v132, v133
	v_cvt_pk_bf16_f32 v133, v134, v135
	global_store_dwordx2 v[6:7], v[132:133], off
	v_lshl_add_u64 v[6:7], v[6:7], 0, s[22:23]
	v_cvt_pk_bf16_f32 v140, v140, v141
	v_cvt_pk_bf16_f32 v141, v142, v143
	global_store_dwordx2 v[16:17], v[140:141], off
	v_lshl_add_u64 v[16:17], v[16:17], 0, s[22:23]
	v_cvt_pk_bf16_f32 v144, v144, v145
	v_cvt_pk_bf16_f32 v145, v146, v147
	global_store_dwordx2 v[20:21], v[144:145], off
	v_lshl_add_u64 v[20:21], v[20:21], 0, s[22:23]
	v_cvt_pk_bf16_f32 v148, v148, v149
	v_cvt_pk_bf16_f32 v149, v150, v151
	global_store_dwordx2 v[6:7], v[148:149], off
	v_lshl_add_u64 v[6:7], v[6:7], 0, s[22:23]
	v_cvt_pk_bf16_f32 v156, v156, v157
	v_cvt_pk_bf16_f32 v157, v158, v159
	global_store_dwordx2 v[16:17], v[156:157], off
	v_lshl_add_u64 v[16:17], v[16:17], 0, s[22:23]
	v_cvt_pk_bf16_f32 v160, v160, v161
	v_cvt_pk_bf16_f32 v161, v162, v163
	global_store_dwordx2 v[20:21], v[160:161], off
	v_lshl_add_u64 v[20:21], v[20:21], 0, s[22:23]
	v_cvt_pk_bf16_f32 v164, v164, v165
	v_cvt_pk_bf16_f32 v165, v166, v167
	global_store_dwordx2 v[6:7], v[164:165], off
	v_lshl_add_u64 v[6:7], v[6:7], 0, s[22:23]
	v_cvt_pk_bf16_f32 v172, v172, v173
	v_cvt_pk_bf16_f32 v173, v174, v175
	global_store_dwordx2 v[16:17], v[172:173], off
	v_lshl_add_u64 v[16:17], v[16:17], 0, s[22:23]
	v_cvt_pk_bf16_f32 v176, v176, v177
	v_cvt_pk_bf16_f32 v177, v178, v179
	global_store_dwordx2 v[20:21], v[176:177], off
	v_lshl_add_u64 v[20:21], v[20:21], 0, s[22:23]
	v_cvt_pk_bf16_f32 v180, v180, v181
	v_cvt_pk_bf16_f32 v181, v182, v183
	global_store_dwordx2 v[6:7], v[180:181], off
	v_lshl_add_u64 v[6:7], v[6:7], 0, s[22:23]
	v_cvt_pk_bf16_f32 v188, v188, v189
	v_cvt_pk_bf16_f32 v189, v190, v191
	global_store_dwordx2 v[16:17], v[188:189], off
	v_lshl_add_u64 v[16:17], v[16:17], 0, s[22:23]
	v_cvt_pk_bf16_f32 v192, v192, v193
	v_cvt_pk_bf16_f32 v193, v194, v195
	global_store_dwordx2 v[20:21], v[192:193], off
	v_lshl_add_u64 v[20:21], v[20:21], 0, s[22:23]
	s_or_b64 exec, exec, s[2:3]
	s_and_saveexec_b64 s[2:3], vcc
	v_cvt_pk_bf16_f32 v136, v136, v137
	v_cvt_pk_bf16_f32 v137, v138, v139
	global_store_dwordx2 v[12:13], v[136:137], off
	v_lshl_add_u64 v[12:13], v[12:13], 0, s[26:27]
	v_cvt_pk_bf16_f32 v152, v152, v153
	v_cvt_pk_bf16_f32 v153, v154, v155
	global_store_dwordx2 v[12:13], v[152:153], off
	v_lshl_add_u64 v[12:13], v[12:13], 0, s[26:27]
	v_cvt_pk_bf16_f32 v168, v168, v169
	v_cvt_pk_bf16_f32 v169, v170, v171
	global_store_dwordx2 v[12:13], v[168:169], off
	v_lshl_add_u64 v[12:13], v[12:13], 0, s[26:27]
	v_cvt_pk_bf16_f32 v184, v184, v185
	v_cvt_pk_bf16_f32 v185, v186, v187
	global_store_dwordx2 v[12:13], v[184:185], off
	v_lshl_add_u64 v[12:13], v[12:13], 0, s[26:27]
	s_or_b64 exec, exec, s[2:3]
	s_mov_b32 s18, 8
	s_branch .LBB0_69
	s_branch .LBB0_58
